# mode-A softmax row sum moved from 4 ones-operand MFMAs per tile to f32 VALU adds (sums f32 p, wider than baseline bf16 p sum)
# baseline (speedup 1.0000x reference)
; __device__ __forceinline__ unsigned pk2(float lo, float hi) { f32x2 v = {lo, hi}; bf16x2_t b = __builtin_convertvector(v, bf16x2_t); return __builtin_bit_cast(unsigned, b); }
; __device__ __forceinline__ float fast_exp2(float x) { return __builtin_amdgcn_exp2f(x); }
; #define MFMA32(a, b, c) __builtin_amdgcn_mfma_f32_32x32x16_bf16((a), (b), (c), 0, 0, 0)
; #define LGKM0() asm volatile("s_waitcnt lgkmcnt(0)" ::: "memory")
; #define SBAR() __builtin_amdgcn_sched_barrier(0)
; #define V_ISSUE(va, b, d) do { _Pragma("unroll") for (int k4 = 0; k4 < 4; ++k4) { DS_TR16(vlo[b][k4], va, (16 * k4) * VP + (d) * 64); DS_TR16(vhi[b][k4], va, (16 * k4 + 8) * VP + (d) * 64); } } while (0)
; template <int DQK, int DV, int MODE>
; __device__ __forceinline__ void attn_item(LAS unsigned char* lds, int item, const AttnCtx& cx) {
;     ...
;         for (int i = 0; i < 16; ++i) { s0[i] = fast_exp2(s0[i]); s1[i] = fast_exp2(s1[i]); }
;         u32x4 w;
;         w.x = pk2(s0[0], s0[1]); w.y = pk2(s0[2], s0[3]); w.z = pk2(s0[4], s0[5]); w.w = pk2(s0[6], s0[7]); pa[0][0] = __builtin_bit_cast(bf16x8, w);
;         w.x = pk2(s0[8], s0[9]); w.y = pk2(s0[10], s0[11]); w.z = pk2(s0[12], s0[13]); w.w = pk2(s0[14], s0[15]); pa[0][1] = __builtin_bit_cast(bf16x8, w);
;         w.x = pk2(s1[0], s1[1]); w.y = pk2(s1[2], s1[3]); w.z = pk2(s1[4], s1[5]); w.w = pk2(s1[6], s1[7]); pa[1][0] = __builtin_bit_cast(bf16x8, w);
;         w.x = pk2(s1[8], s1[9]); w.y = pk2(s1[10], s1[11]); w.z = pk2(s1[12], s1[13]); w.w = pk2(s1[14], s1[15]); pa[1][1] = __builtin_bit_cast(bf16x8, w);
;     };
;     auto do_pv = [&](unsigned va) {
; #pragma unroll
;         for (int k4 = 0; k4 < 4; ++k4) Lacc = MFMA32(ones8, pa[k4 >> 1][k4 & 1], Lacc);
; #pragma unroll
;         for (int d = 0; d < NDV; ++d) {
;             LGKM0(); SBAR();
; #pragma unroll
;             for (int k4 = 0; k4 < 4; ++k4) {
;                 const bf16x8 vf = __builtin_shufflevector(vlo[d & 1][k4], vhi[d & 1][k4], 0, 1, 2, 3, 4, 5, 6, 7);
;                 O[d] = MFMA32(vf, pa[k4 >> 1][k4 & 1], O[d]);
;             }
;             SBAR();
;             if (d + 1 < NDV) V_ISSUE(va, (d + 1) & 1, d + 1);
;         }
;     ...
;             if (!rot || j == 0) do_qk(j, !rot);
;             if (rot) V_ISSUE(vaddr_of(j), 0, 0);
;             do_soft(j);
;             do_pv(vaddr_of(j));
;             if (rot && j + 1 < ntiles) do_qk(j + 1, false);
.LBB0_257:
	s_mov_b32 s90, s88
	s_mov_b32 s91, s88
	s_mov_b32 s89, s88
	v_mov_b64_e32 v[228:229], s[90:91]
	v_exp_f32_e32 v82, v82
	v_exp_f32_e32 v83, v83
	v_exp_f32_e32 v84, v84
	v_exp_f32_e32 v85, v85
	v_exp_f32_e32 v86, v86
	v_exp_f32_e32 v87, v87
	v_exp_f32_e32 v88, v88
	v_exp_f32_e32 v89, v89
	v_mov_b64_e32 v[226:227], s[88:89]
	v_cvt_pk_bf16_f32 v230, v82, v83
	v_cvt_pk_bf16_f32 v231, v84, v85
	v_cvt_pk_bf16_f32 v232, v86, v87
	v_cvt_pk_bf16_f32 v233, v88, v89
	v_exp_f32_e32 v90, v90
	v_exp_f32_e32 v91, v91
	v_add_f32_e32 v66, v66, v82
	v_add_f32_e32 v67, v67, v83
	v_add_f32_e32 v68, v68, v84
	v_add_f32_e32 v69, v69, v85
	v_add_f32_e32 v66, v66, v86
	v_add_f32_e32 v67, v67, v87
	v_add_f32_e32 v68, v68, v88
	v_add_f32_e32 v69, v69, v89
	v_exp_f32_e32 v92, v92
	v_exp_f32_e32 v93, v93
	v_exp_f32_e32 v94, v94
	v_exp_f32_e32 v95, v95
	v_exp_f32_e32 v96, v96
	v_exp_f32_e32 v97, v97
	v_cvt_pk_bf16_f32 v234, v90, v91
	v_cvt_pk_bf16_f32 v235, v92, v93
	v_cvt_pk_bf16_f32 v236, v94, v95
	v_cvt_pk_bf16_f32 v237, v96, v97
	v_exp_f32_e32 v98, v98
	v_exp_f32_e32 v99, v99
	v_add_f32_e32 v66, v66, v90
	v_add_f32_e32 v67, v67, v91
	v_add_f32_e32 v68, v68, v92
	v_add_f32_e32 v69, v69, v93
	v_add_f32_e32 v66, v66, v94
	v_add_f32_e32 v67, v67, v95
	v_add_f32_e32 v68, v68, v96
	v_add_f32_e32 v69, v69, v97
	v_exp_f32_e32 v100, v100
	v_exp_f32_e32 v101, v101
	v_exp_f32_e32 v102, v102
	v_exp_f32_e32 v103, v103
	v_exp_f32_e32 v104, v104
	v_exp_f32_e32 v105, v105
	v_cvt_pk_bf16_f32 v238, v98, v99
	v_cvt_pk_bf16_f32 v239, v100, v101
	v_cvt_pk_bf16_f32 v240, v102, v103
	v_cvt_pk_bf16_f32 v241, v104, v105
	v_exp_f32_e32 v106, v106
	v_exp_f32_e32 v107, v107
	v_add_f32_e32 v66, v66, v98
	v_add_f32_e32 v67, v67, v99
	v_add_f32_e32 v68, v68, v100
	v_add_f32_e32 v69, v69, v101
	v_add_f32_e32 v66, v66, v102
	v_add_f32_e32 v67, v67, v103
	v_add_f32_e32 v68, v68, v104
	v_add_f32_e32 v69, v69, v105
	v_exp_f32_e32 v108, v108
	v_exp_f32_e32 v109, v109
	v_exp_f32_e32 v110, v110
	v_exp_f32_e32 v111, v111
	v_exp_f32_e32 v112, v112
	v_exp_f32_e32 v113, v113
	v_cvt_pk_bf16_f32 v242, v106, v107
	v_cvt_pk_bf16_f32 v243, v108, v109
	v_cvt_pk_bf16_f32 v244, v110, v111
	v_cvt_pk_bf16_f32 v245, v112, v113
	s_and_b32 s3, s82, 3
	s_mul_i32 s3, s3, 0x9800
	v_add_f32_e32 v66, v66, v106
	v_add_f32_e32 v67, v67, v107
	v_add_f32_e32 v68, v68, v108
	v_add_f32_e32 v69, v69, v109
	v_add_f32_e32 v66, v66, v110
	v_add_f32_e32 v67, v67, v111
	v_add_f32_e32 v68, v68, v112
	v_add_f32_e32 v69, v69, v113
	s_waitcnt lgkmcnt(0)
	s_add_i32 s3, s3, 0
	s_addk_i32 s3, 0x4800
	v_add_u32_e32 v213, s3, v203
	v_mfma_f32_32x32x16_bf16 v[50:65], v[162:165], v[230:233], v[50:65]
	v_mfma_f32_32x32x16_bf16 v[50:65], v[166:169], v[234:237], v[50:65]
	v_mfma_f32_32x32x16_bf16 v[50:65], v[170:173], v[238:241], v[50:65]
	v_mfma_f32_32x32x16_bf16 v[50:65], v[174:177], v[242:245], v[50:65]
	ds_read_b64_tr_b16 v[162:163], v213 offset:64
	ds_read_b64_tr_b16 v[164:165], v213 offset:2624
	ds_read_b64_tr_b16 v[166:167], v213 offset:5184
	ds_read_b64_tr_b16 v[168:169], v213 offset:7744
	ds_read_b64_tr_b16 v[170:171], v213 offset:10304
	ds_read_b64_tr_b16 v[172:173], v213 offset:12864
	ds_read_b64_tr_b16 v[174:175], v213 offset:15424
	ds_read_b64_tr_b16 v[176:177], v213 offset:17984
	s_waitcnt lgkmcnt(0)
	s_nop 0
	v_mfma_f32_32x32x16_bf16 v[34:49], v[162:165], v[230:233], v[34:49]
	v_mfma_f32_32x32x16_bf16 v[34:49], v[166:169], v[234:237], v[34:49]
	v_mfma_f32_32x32x16_bf16 v[34:49], v[170:173], v[238:241], v[34:49]
	v_mfma_f32_32x32x16_bf16 v[34:49], v[174:177], v[242:245], v[34:49]
	ds_read_b64_tr_b16 v[162:163], v213 offset:128
	ds_read_b64_tr_b16 v[164:165], v213 offset:2688
	ds_read_b64_tr_b16 v[166:167], v213 offset:5248
	ds_read_b64_tr_b16 v[168:169], v213 offset:7808
	ds_read_b64_tr_b16 v[170:171], v213 offset:10368
	ds_read_b64_tr_b16 v[172:173], v213 offset:12928
	ds_read_b64_tr_b16 v[174:175], v213 offset:15488
	ds_read_b64_tr_b16 v[176:177], v213 offset:18048
	s_waitcnt lgkmcnt(0)
	s_nop 0
	v_mfma_f32_32x32x16_bf16 v[18:33], v[162:165], v[230:233], v[18:33]
	v_mfma_f32_32x32x16_bf16 v[18:33], v[166:169], v[234:237], v[18:33]
	v_mfma_f32_32x32x16_bf16 v[18:33], v[170:173], v[238:241], v[18:33]
	v_mfma_f32_32x32x16_bf16 v[18:33], v[174:177], v[242:245], v[18:33]
	ds_read_b64_tr_b16 v[226:227], v213 offset:192
	ds_read_b64_tr_b16 v[228:229], v213 offset:2752
	ds_read_b64_tr_b16 v[246:247], v213 offset:5312
	ds_read_b64_tr_b16 v[248:249], v213 offset:7872
	ds_read_b64_tr_b16 v[222:223], v213 offset:10432
	ds_read_b64_tr_b16 v[224:225], v213 offset:12992
	ds_read_b64_tr_b16 v[214:215], v213 offset:15552
	ds_read_b64_tr_b16 v[216:217], v213 offset:18112
	s_waitcnt lgkmcnt(0)
	s_nop 0
	v_mfma_f32_32x32x16_bf16 v[2:17], v[226:229], v[230:233], v[2:17]
	v_mfma_f32_32x32x16_bf16 v[2:17], v[246:249], v[234:237], v[2:17]
	v_mfma_f32_32x32x16_bf16 v[2:17], v[222:225], v[238:241], v[2:17]
	v_mfma_f32_32x32x16_bf16 v[2:17], v[214:217], v[242:245], v[2:17]
	s_add_i32 s82, s82, 1
	s_cmp_ge_u32 s82, s83
	s_cselect_b64 s[50:51], -1, 0
	s_or_b64 s[50:51], s[24:25], s[50:51]
	s_and_b64 vcc, exec, s[50:51]
	s_cbranch_vccnz .LBB0_200
	s_and_b32 s3, s82, 3
	s_mul_i32 s3, s3, 0x9800
	s_add_i32 s3, s77, s3
	v_add_u32_e32 v213, s3, v202
	ds_read_b128 v[98:101], v213 offset:0
	ds_read_b128 v[102:105], v213 offset:4608
	ds_read_b128 v[106:109], v213 offset:32
	ds_read_b128 v[110:113], v213 offset:4640
	s_waitcnt lgkmcnt(0)
	s_nop 0
	v_mfma_f32_32x32x16_bf16 v[82:97], v[98:101], v[146:149], v[130:145]
	v_mfma_f32_32x32x16_bf16 v[130:145], v[102:105], v[146:149], v[130:145]
	v_mfma_f32_32x32x16_bf16 v[82:97], v[106:109], v[150:153], v[82:97]
	v_mfma_f32_32x32x16_bf16 v[130:145], v[110:113], v[150:153], v[130:145]
	ds_read_b128 v[98:101], v213 offset:64
	ds_read_b128 v[102:105], v213 offset:4672
	ds_read_b128 v[106:109], v213 offset:96
	ds_read_b128 v[110:113], v213 offset:4704
	s_waitcnt lgkmcnt(0)
	s_nop 0
	v_mfma_f32_32x32x16_bf16 v[82:97], v[98:101], v[154:157], v[82:97]
	v_mfma_f32_32x32x16_bf16 v[130:145], v[102:105], v[154:157], v[130:145]
	v_mfma_f32_32x32x16_bf16 v[82:97], v[106:109], v[158:161], v[82:97]
	v_mfma_f32_32x32x16_bf16 v[130:145], v[110:113], v[158:161], v[130:145]
	s_nop 11
	v_mov_b32_e32 v98, v130
	v_mov_b32_e32 v99, v131
	v_mov_b32_e32 v100, v132
	v_mov_b32_e32 v101, v133
	v_mov_b32_e32 v102, v134
	v_mov_b32_e32 v103, v135
	v_mov_b32_e32 v104, v136
	v_mov_b32_e32 v105, v137
	v_mov_b32_e32 v106, v138
	v_mov_b32_e32 v107, v139
	v_mov_b32_e32 v108, v140
	v_mov_b32_e32 v109, v141
	v_mov_b32_e32 v110, v142
	v_mov_b32_e32 v111, v143
	v_mov_b32_e32 v112, v144
	v_mov_b32_e32 v113, v145
	s_branch .LBB0_200

; #define LAS __attribute__((address_space(3)))
; template <int DQK, int DV, int MODE>
; __device__ __forceinline__ void attn_item(LAS unsigned char* lds, int item, const AttnCtx& cx) {
;     ...
;     const float lt = Lacc[0];
;     const float inv = 1.f / lt;
;     if (DMA) __syncthreads();
;     if (MODE == 0) {
;         LAS float* X = (LAS float*)lds;
;         if (hf == 1) {
; #pragma unroll
;             for (int d = 0; d < NDV; ++d)
; #pragma unroll
;                 for (int g4 = 0; g4 < 4; ++g4) {
;                     f32x4 v = {O[d][4 * g4] * inv, O[d][4 * g4 + 1] * inv, O[d][4 * g4 + 2] * inv, O[d][4 * g4 + 3] * inv};
;                     *(LAS f32x4*)(X + (32 * wq + r) * 132 + 32 * d + 8 * g4 + 4 * h) = v;
;                 }
;         }
.LBB0_268:
	v_add_f32_e32 v66, v66, v67
	v_add_f32_e32 v68, v68, v69
	s_nop 0
	v_add_f32_e32 v66, v66, v68
	s_nop 0
	v_mov_b32_e32 v67, v66
	s_nop 1
	v_permlane32_swap_b32_e32 v66, v67
	s_nop 1
	v_add_f32_e32 v66, v66, v67
	v_div_scale_f32 v67, s[22:23], v66, v66, 1.0
	v_rcp_f32_e32 v68, v67
	v_div_scale_f32 v69, vcc, 1.0, v66, 1.0
	s_waitcnt vmcnt(0) lgkmcnt(0)
	v_fma_f32 v70, -v67, v68, 1.0
	v_fmac_f32_e32 v68, v70, v68
	v_mul_f32_e32 v70, v69, v68
	v_fma_f32 v71, -v67, v70, v69
	v_fmac_f32_e32 v70, v71, v68
	v_fma_f32 v67, -v67, v70, v69
	v_div_fmas_f32 v67, v67, v68, v70
	v_div_fixup_f32 v136, v67, v66, 1.0
	s_and_b64 vcc, exec, s[46:47]
	s_barrier
	s_cbranch_vccnz .LBB0_270
	v_lshl_or_b32 v66, s30, 5, v201
	v_mul_u32_u24_e32 v66, 0x210, v66
	v_add3_u32 v70, 0, v66, v0
	v_pk_mul_f32 v[66:67], v[136:137], v[50:51] op_sel_hi:[0,1]
	v_pk_mul_f32 v[68:69], v[136:137], v[52:53] op_sel_hi:[0,1]
	ds_write_b128 v70, v[66:69]
	v_pk_mul_f32 v[66:67], v[136:137], v[54:55] op_sel_hi:[0,1]
	v_pk_mul_f32 v[68:69], v[136:137], v[56:57] op_sel_hi:[0,1]
	ds_write_b128 v70, v[66:69] offset:32
	v_pk_mul_f32 v[66:67], v[136:137], v[58:59] op_sel_hi:[0,1]
	v_pk_mul_f32 v[68:69], v[136:137], v[60:61] op_sel_hi:[0,1]
	ds_write_b128 v70, v[66:69] offset:64
	v_pk_mul_f32 v[66:67], v[136:137], v[62:63] op_sel_hi:[0,1]
	v_pk_mul_f32 v[68:69], v[136:137], v[64:65] op_sel_hi:[0,1]
	ds_write_b128 v70, v[66:69] offset:96
	v_pk_mul_f32 v[66:67], v[136:137], v[34:35] op_sel_hi:[0,1]
	v_pk_mul_f32 v[68:69], v[136:137], v[36:37] op_sel_hi:[0,1]
	ds_write_b128 v70, v[66:69] offset:128
	v_pk_mul_f32 v[66:67], v[136:137], v[38:39] op_sel_hi:[0,1]
	v_pk_mul_f32 v[68:69], v[136:137], v[40:41] op_sel_hi:[0,1]
	ds_write_b128 v70, v[66:69] offset:160
	v_pk_mul_f32 v[66:67], v[136:137], v[42:43] op_sel_hi:[0,1]
	v_pk_mul_f32 v[68:69], v[136:137], v[44:45] op_sel_hi:[0,1]
	ds_write_b128 v70, v[66:69] offset:192
	v_pk_mul_f32 v[66:67], v[136:137], v[46:47] op_sel_hi:[0,1]
	v_pk_mul_f32 v[68:69], v[136:137], v[48:49] op_sel_hi:[0,1]
	ds_write_b128 v70, v[66:69] offset:224
	v_pk_mul_f32 v[66:67], v[136:137], v[18:19] op_sel_hi:[0,1]
	v_pk_mul_f32 v[68:69], v[136:137], v[20:21] op_sel_hi:[0,1]
	ds_write_b128 v70, v[66:69] offset:256
	v_pk_mul_f32 v[66:67], v[136:137], v[22:23] op_sel_hi:[0,1]
	v_pk_mul_f32 v[68:69], v[136:137], v[24:25] op_sel_hi:[0,1]
	ds_write_b128 v70, v[66:69] offset:288
	v_pk_mul_f32 v[66:67], v[136:137], v[26:27] op_sel_hi:[0,1]
	v_pk_mul_f32 v[68:69], v[136:137], v[28:29] op_sel_hi:[0,1]
	ds_write_b128 v70, v[66:69] offset:320
	v_pk_mul_f32 v[66:67], v[136:137], v[30:31] op_sel_hi:[0,1]
	v_pk_mul_f32 v[68:69], v[136:137], v[32:33] op_sel_hi:[0,1]
	ds_write_b128 v70, v[66:69] offset:352
	v_pk_mul_f32 v[66:67], v[136:137], v[2:3] op_sel_hi:[0,1]
	v_pk_mul_f32 v[68:69], v[136:137], v[4:5] op_sel_hi:[0,1]
	ds_write_b128 v70, v[66:69] offset:384
	v_pk_mul_f32 v[66:67], v[136:137], v[6:7] op_sel_hi:[0,1]
	v_pk_mul_f32 v[68:69], v[136:137], v[8:9] op_sel_hi:[0,1]
	ds_write_b128 v70, v[66:69] offset:416
	v_pk_mul_f32 v[66:67], v[136:137], v[10:11] op_sel_hi:[0,1]
	v_pk_mul_f32 v[68:69], v[136:137], v[12:13] op_sel_hi:[0,1]
	ds_write_b128 v70, v[66:69] offset:448
	v_pk_mul_f32 v[66:67], v[136:137], v[14:15] op_sel_hi:[0,1]
	v_pk_mul_f32 v[68:69], v[136:137], v[16:17] op_sel_hi:[0,1]
	ds_write_b128 v70, v[66:69] offset:480
